# combined layout changes; generic-grid conversion copy patched consistently as well
# baseline (speedup 1.0000x reference)
.LBB0_299:
	v_readlane_b32 s14, v250, 56
	s_add_i32 s18, s18, s14
	s_cmpk_gt_i32 s18, 0x3af
	v_readlane_b32 s15, v250, 57
	s_cbranch_scc1 .LBB0_315

.LBB0_307:
	s_andn2_b64 vcc, exec, s[16:17]
	s_cbranch_vccnz .LBB0_309
	s_add_i32 s16, s20, 0xffffe500
	s_lshr_b32 s16, s16, 2
	s_and_b32 s17, s16, 0x3fffffc0
	s_lshl_b32 s16, s20, 5
	s_and_b32 s16, s16, 0x1fe0
	v_add_u32_e32 v22, s17, v1
	s_lshl_b32 s90, s16, 2
	v_ashrrev_i32_e32 v23, 31, v22
	v_lshl_add_u64 v[32:33], v[6:7], 0, s[90:91]
	v_lshlrev_b64 v[22:23], 15, v[22:23]
	v_lshl_add_u64 v[22:23], v[32:33], 0, v[22:23]
	v_add_co_u32_e32 v32, vcc, 0x10000, v22
	global_load_dword v3, v[22:23], off nt
	s_nop 0
	v_addc_co_u32_e32 v33, vcc, 0, v23, vcc
	global_load_dword v9, v[32:33], off nt
	v_add_co_u32_e32 v32, vcc, 0x20000, v22
	s_lshl_b32 s90, s17, 1
	s_nop 0
	v_addc_co_u32_e32 v33, vcc, 0, v23, vcc
	global_load_dword v18, v[32:33], off nt
	v_add_co_u32_e32 v32, vcc, 0x30000, v22
	s_nop 1
	v_addc_co_u32_e32 v33, vcc, 0, v23, vcc
	global_load_dword v31, v[32:33], off nt
	v_add_co_u32_e32 v32, vcc, 0x40000, v22
	s_nop 1
	v_addc_co_u32_e32 v33, vcc, 0, v23, vcc
	global_load_dword v34, v[32:33], off nt
	v_add_co_u32_e32 v32, vcc, 0x50000, v22
	s_nop 1
	v_addc_co_u32_e32 v33, vcc, 0, v23, vcc
	global_load_dword v35, v[32:33], off nt
	v_add_co_u32_e32 v32, vcc, 0x60000, v22
	s_nop 1
	v_addc_co_u32_e32 v33, vcc, 0, v23, vcc
	global_load_dword v36, v[32:33], off nt
	v_add_co_u32_e32 v32, vcc, 0x70000, v22
	s_nop 1
	v_addc_co_u32_e32 v33, vcc, 0, v23, vcc
	global_load_dword v37, v[32:33], off nt
	v_add_co_u32_e32 v32, vcc, 0x80000, v22
	s_nop 1
	v_addc_co_u32_e32 v33, vcc, 0, v23, vcc
	global_load_dword v38, v[32:33], off nt
	v_add_co_u32_e32 v32, vcc, 0x90000, v22
	s_nop 1
	v_addc_co_u32_e32 v33, vcc, 0, v23, vcc
	global_load_dword v39, v[32:33], off nt
	v_add_co_u32_e32 v32, vcc, 0xa0000, v22
	s_nop 1
	v_addc_co_u32_e32 v33, vcc, 0, v23, vcc
	global_load_dword v40, v[32:33], off nt
	v_add_co_u32_e32 v32, vcc, 0xb0000, v22
	s_nop 1
	v_addc_co_u32_e32 v33, vcc, 0, v23, vcc
	global_load_dword v41, v[32:33], off nt
	v_add_co_u32_e32 v32, vcc, 0xc0000, v22
	s_nop 1
	v_addc_co_u32_e32 v33, vcc, 0, v23, vcc
	global_load_dword v42, v[32:33], off nt
	v_add_co_u32_e32 v32, vcc, 0xd0000, v22
	s_nop 1
	v_addc_co_u32_e32 v33, vcc, 0, v23, vcc
	global_load_dword v43, v[32:33], off nt
	v_add_co_u32_e32 v32, vcc, 0xe0000, v22
	s_nop 1
	v_addc_co_u32_e32 v33, vcc, 0, v23, vcc
	global_load_dword v44, v[32:33], off nt
	v_add_co_u32_e32 v32, vcc, 0xf0000, v22
	s_nop 1
	v_addc_co_u32_e32 v33, vcc, 0, v23, vcc
	global_load_dword v45, v[32:33], off nt
	v_add_co_u32_e32 v32, vcc, 0x100000, v22
	s_nop 1
	v_addc_co_u32_e32 v33, vcc, 0, v23, vcc
	global_load_dword v46, v[32:33], off nt
	v_add_co_u32_e32 v32, vcc, 0x110000, v22
	s_nop 1
	v_addc_co_u32_e32 v33, vcc, 0, v23, vcc
	global_load_dword v47, v[32:33], off nt
	v_add_co_u32_e32 v32, vcc, 0x120000, v22
	s_nop 1
	v_addc_co_u32_e32 v33, vcc, 0, v23, vcc
	global_load_dword v48, v[32:33], off nt
	v_add_co_u32_e32 v32, vcc, 0x130000, v22
	s_nop 1
	v_addc_co_u32_e32 v33, vcc, 0, v23, vcc
	global_load_dword v49, v[32:33], off nt
	v_add_co_u32_e32 v32, vcc, 0x140000, v22
	s_nop 1
	v_addc_co_u32_e32 v33, vcc, 0, v23, vcc
	global_load_dword v50, v[32:33], off nt
	v_add_co_u32_e32 v32, vcc, 0x150000, v22
	s_nop 1
	v_addc_co_u32_e32 v33, vcc, 0, v23, vcc
	global_load_dword v51, v[32:33], off nt
	v_add_co_u32_e32 v32, vcc, 0x160000, v22
	s_nop 1
	v_addc_co_u32_e32 v33, vcc, 0, v23, vcc
	global_load_dword v52, v[32:33], off nt
	v_add_co_u32_e32 v32, vcc, 0x170000, v22
	s_nop 1
	v_addc_co_u32_e32 v33, vcc, 0, v23, vcc
	global_load_dword v53, v[32:33], off nt
	v_add_co_u32_e32 v32, vcc, 0x180000, v22
	s_nop 1
	v_addc_co_u32_e32 v33, vcc, 0, v23, vcc
	global_load_dword v54, v[32:33], off nt
	v_add_co_u32_e32 v32, vcc, 0x190000, v22
	s_nop 1
	v_addc_co_u32_e32 v33, vcc, 0, v23, vcc
	global_load_dword v55, v[32:33], off nt
	v_add_co_u32_e32 v32, vcc, 0x1a0000, v22
	s_nop 1
	v_addc_co_u32_e32 v33, vcc, 0, v23, vcc
	global_load_dword v56, v[32:33], off nt
	v_add_co_u32_e32 v32, vcc, 0x1b0000, v22
	s_nop 1
	v_addc_co_u32_e32 v33, vcc, 0, v23, vcc
	global_load_dword v57, v[32:33], off nt
	v_add_co_u32_e32 v32, vcc, 0x1c0000, v22
	s_nop 1
	v_addc_co_u32_e32 v33, vcc, 0, v23, vcc
	global_load_dword v58, v[32:33], off nt
	v_add_co_u32_e32 v32, vcc, 0x1d0000, v22
	s_nop 1
	v_addc_co_u32_e32 v33, vcc, 0, v23, vcc
	global_load_dword v59, v[32:33], off nt
	v_add_co_u32_e32 v32, vcc, 0x1e0000, v22
	s_nop 1
	v_addc_co_u32_e32 v33, vcc, 0, v23, vcc
	v_add_co_u32_e32 v22, vcc, 0x1f0000, v22
	global_load_dword v32, v[32:33], off nt
	s_nop 0
	v_addc_co_u32_e32 v23, vcc, 0, v23, vcc
	global_load_dword v22, v[22:23], off nt
	s_waitcnt vmcnt(0)
	ds_write2_b32 v24, v3, v9 offset1:66
	ds_write2_b32 v24, v18, v31 offset0:132 offset1:198
	v_add_u32_e32 v3, 0x400, v24
	ds_write2_b32 v3, v34, v35 offset0:8 offset1:74
	ds_write2_b32 v3, v36, v37 offset0:140 offset1:206
	v_add_u32_e32 v3, 0x800, v24
	ds_write2_b32 v3, v38, v39 offset0:16 offset1:82
	ds_write2_b32 v3, v40, v41 offset0:148 offset1:214
	v_add_u32_e32 v3, 0xc00, v24
	ds_write2_b32 v3, v42, v43 offset0:24 offset1:90
	ds_write2_b32 v3, v44, v45 offset0:156 offset1:222
	v_add_u32_e32 v3, 0x1000, v24
	ds_write2_b32 v3, v46, v47 offset0:32 offset1:98
	ds_write2_b32 v3, v48, v49 offset0:164 offset1:230
	v_add_u32_e32 v3, 0x1400, v24
	ds_write2_b32 v3, v50, v51 offset0:40 offset1:106
	ds_write2_b32 v3, v52, v53 offset0:172 offset1:238
	v_add_u32_e32 v3, 0x1800, v24
	ds_write2_b32 v3, v54, v55 offset0:48 offset1:114
	ds_write2_b32 v3, v56, v57 offset0:180 offset1:246
	v_add_u32_e32 v3, 0x1c00, v24
	ds_write2_b32 v3, v58, v59 offset0:56 offset1:122
	ds_write2_b32 v3, v32, v22 offset0:188 offset1:254
	s_waitcnt lgkmcnt(0)
	v_and_b32_e32 v70, 3, v146
	v_mul_u32_u24_e32 v70, 0x420, v70
	v_lshrrev_b32_e32 v71, 4, v146
	v_lshl_add_u32 v70, v71, 5, v70
	v_bfe_u32 v71, v146, 2, 2
	v_lshl_add_u32 v70, v71, 2, v70
	s_lshl_b32 s100, s49, 14
	v_add_u32_e32 v70, s100, v70
	v_add_u32_e32 v71, 0x1080, v70
	ds_read2_b32 v[36:37], v70 offset0:33 offset1:37
	ds_read2_b32 v[38:39], v70 offset1:4
	ds_read2_b32 v[40:41], v70 offset0:66 offset1:70
	ds_read2_b32 v[42:43], v70 offset0:99 offset1:103
	ds_read2_b32 v[44:45], v70 offset0:132 offset1:136
	ds_read2_b32 v[46:47], v70 offset0:165 offset1:169
	ds_read2_b32 v[48:49], v70 offset0:198 offset1:202
	ds_read2_b32 v[50:51], v70 offset0:231 offset1:235
	s_waitcnt lgkmcnt(7)
	v_bfe_u32 v9, v36, 16, 1
	s_waitcnt lgkmcnt(6)
	v_bfe_u32 v3, v38, 16, 1
	v_add3_u32 v3, v38, v3, s79
	v_lshrrev_b32_e32 v3, 16, v3
	v_add3_u32 v9, v36, v9, s79
	v_and_or_b32 v32, v9, s80, v3
	s_waitcnt lgkmcnt(5)
	v_bfe_u32 v3, v40, 16, 1
	v_add3_u32 v3, v40, v3, s79
	s_waitcnt lgkmcnt(4)
	v_bfe_u32 v9, v42, 16, 1
	v_lshrrev_b32_e32 v3, 16, v3
	v_add3_u32 v9, v42, v9, s79
	v_and_or_b32 v33, v9, s80, v3
	s_waitcnt lgkmcnt(3)
	v_bfe_u32 v3, v44, 16, 1
	v_add3_u32 v3, v44, v3, s79
	s_waitcnt lgkmcnt(2)
	v_bfe_u32 v9, v46, 16, 1
	v_lshrrev_b32_e32 v3, 16, v3
	v_add3_u32 v9, v46, v9, s79
	v_and_or_b32 v34, v9, s80, v3
	s_waitcnt lgkmcnt(1)
	v_bfe_u32 v3, v48, 16, 1
	v_add3_u32 v3, v48, v3, s79
	s_waitcnt lgkmcnt(0)
	v_bfe_u32 v9, v50, 16, 1
	v_lshrrev_b32_e32 v3, 16, v3
	v_add3_u32 v9, v50, v9, s79
	v_add_u32_e32 v52, s16, v25
	v_and_or_b32 v35, v9, s80, v3
	v_ashrrev_i32_e32 v53, 31, v52
	v_bfe_u32 v3, v39, 16, 1
	v_lshl_add_u64 v[22:23], v[10:11], 0, s[90:91]
	s_lshl_b32 s100, s90, 8
	s_lshr_b32 s101, s16, 8
	s_lshl_b32 s101, s101, 20
	s_add_i32 s100, s100, s101
	s_bfe_u32 s101, s16, 0x10007
	s_lshl_b32 s101, s101, 14
	s_add_i32 s100, s100, s101
	s_bfe_u32 s101, s16, 0x20005
	s_lshl_b32 s101, s101, 12
	s_add_i32 s100, s100, s101
	v_lshrrev_b32_e32 v62, 5, v146
	v_lshlrev_b32_e32 v62, 5, v62
	v_lshlrev_b32_e32 v64, 4, v146
	v_xor_b32_e32 v62, v62, v64
	v_add_u32_e32 v62, s100, v62
	v_mov_b32_e32 v63, v19
	v_sub_u32_e32 v68, 0, v8
	v_ashrrev_i32_e32 v69, 31, v68
	v_lshl_add_u64 v[66:67], v[10:11], 0, v[68:69]
	v_lshl_add_u64 v[68:69], v[66:67], 0, v[62:63]
	v_lshlrev_b64 v[52:53], 12, v[52:53]
	v_add3_u32 v3, v39, v3, s79
	v_bfe_u32 v9, v37, 16, 1
	v_lshl_add_u64 v[52:53], v[22:23], 0, v[52:53]
	v_lshrrev_b32_e32 v3, 16, v3
	v_add3_u32 v9, v37, v9, s79
	global_store_dwordx4 v[68:69], v[32:35], off nt
	v_add_u32_e32 v36, s16, v27
	v_ashrrev_i32_e32 v37, 31, v36
	v_and_or_b32 v32, v9, s80, v3
	v_bfe_u32 v3, v41, 16, 1
	v_add3_u32 v3, v41, v3, s79
	v_bfe_u32 v9, v43, 16, 1
	v_lshrrev_b32_e32 v3, 16, v3
	v_add3_u32 v9, v43, v9, s79
	v_and_or_b32 v33, v9, s80, v3
	v_bfe_u32 v3, v45, 16, 1
	v_add3_u32 v3, v45, v3, s79
	v_bfe_u32 v9, v47, 16, 1
	v_lshrrev_b32_e32 v3, 16, v3
	v_add3_u32 v9, v47, v9, s79
	v_and_or_b32 v34, v9, s80, v3
	v_bfe_u32 v3, v49, 16, 1
	v_add3_u32 v3, v49, v3, s79
	v_bfe_u32 v9, v51, 16, 1
	v_lshrrev_b32_e32 v3, 16, v3
	v_add3_u32 v9, v51, v9, s79
	v_lshlrev_b64 v[36:37], 12, v[36:37]
	v_and_or_b32 v35, v9, s80, v3
	v_lshl_add_u64 v[36:37], v[22:23], 0, v[36:37]
	global_store_dwordx4 v[68:69], v[32:35], off offset:2048 nt
	ds_read2_b32 v[36:37], v71 offset0:33 offset1:37
	ds_read2_b32 v[38:39], v71 offset1:4
	ds_read2_b32 v[40:41], v71 offset0:66 offset1:70
	ds_read2_b32 v[42:43], v71 offset0:99 offset1:103
	ds_read2_b32 v[44:45], v71 offset0:132 offset1:136
	ds_read2_b32 v[46:47], v71 offset0:165 offset1:169
	ds_read2_b32 v[48:49], v71 offset0:198 offset1:202
	ds_read2_b32 v[50:51], v71 offset0:231 offset1:235
	s_waitcnt lgkmcnt(7)
	v_bfe_u32 v9, v36, 16, 1
	s_waitcnt lgkmcnt(6)
	v_bfe_u32 v3, v38, 16, 1
	v_add3_u32 v3, v38, v3, s79
	v_lshrrev_b32_e32 v3, 16, v3
	v_add3_u32 v9, v36, v9, s79
	v_and_or_b32 v32, v9, s80, v3
	s_waitcnt lgkmcnt(5)
	v_bfe_u32 v3, v40, 16, 1
	v_add3_u32 v3, v40, v3, s79
	s_waitcnt lgkmcnt(4)
	v_bfe_u32 v9, v42, 16, 1
	v_lshrrev_b32_e32 v3, 16, v3
	v_add3_u32 v9, v42, v9, s79
	v_and_or_b32 v33, v9, s80, v3
	s_waitcnt lgkmcnt(3)
	v_bfe_u32 v3, v44, 16, 1
	v_add3_u32 v3, v44, v3, s79
	s_waitcnt lgkmcnt(2)
	v_bfe_u32 v9, v46, 16, 1
	v_lshrrev_b32_e32 v3, 16, v3
	v_add3_u32 v9, v46, v9, s79
	v_and_or_b32 v34, v9, s80, v3
	s_waitcnt lgkmcnt(1)
	v_bfe_u32 v3, v48, 16, 1
	v_add3_u32 v3, v48, v3, s79
	s_waitcnt lgkmcnt(0)
	v_bfe_u32 v9, v50, 16, 1
	v_lshrrev_b32_e32 v3, 16, v3
	v_add3_u32 v9, v50, v9, s79
	v_add_u32_e32 v52, s16, v28
	v_and_or_b32 v35, v9, s80, v3
	v_ashrrev_i32_e32 v53, 31, v52
	v_bfe_u32 v3, v39, 16, 1
	v_lshlrev_b64 v[52:53], 12, v[52:53]
	v_add3_u32 v3, v39, v3, s79
	v_bfe_u32 v9, v37, 16, 1
	v_lshl_add_u64 v[52:53], v[22:23], 0, v[52:53]
	v_lshrrev_b32_e32 v3, 16, v3
	v_add3_u32 v9, v37, v9, s79
	global_store_dwordx4 v[68:69], v[32:35], off offset:1024 nt
	v_add_u32_e32 v36, s16, v29
	v_ashrrev_i32_e32 v37, 31, v36
	v_and_or_b32 v32, v9, s80, v3
	v_bfe_u32 v3, v41, 16, 1
	v_add3_u32 v3, v41, v3, s79
	v_bfe_u32 v9, v43, 16, 1
	v_lshrrev_b32_e32 v3, 16, v3
	v_add3_u32 v9, v43, v9, s79
	v_and_or_b32 v33, v9, s80, v3
	v_bfe_u32 v3, v45, 16, 1
	v_add3_u32 v3, v45, v3, s79
	v_bfe_u32 v9, v47, 16, 1
	v_lshrrev_b32_e32 v3, 16, v3
	v_add3_u32 v9, v47, v9, s79
	v_and_or_b32 v34, v9, s80, v3
	v_bfe_u32 v3, v49, 16, 1
	v_add3_u32 v3, v49, v3, s79
	v_bfe_u32 v9, v51, 16, 1
	v_lshrrev_b32_e32 v3, 16, v3
	v_add3_u32 v9, v51, v9, s79
	v_lshlrev_b64 v[36:37], 12, v[36:37]
	v_and_or_b32 v35, v9, s80, v3
	v_lshl_add_u64 v[22:23], v[22:23], 0, v[36:37]
	global_store_dwordx4 v[68:69], v[32:35], off offset:3072 nt
	s_waitcnt lgkmcnt(0)
